# v59 plus: workgroups with bit 3 of blockIdx.x set run the RG-LRU pass-1 units before the attention units inside P2 (other half keeps the compiled order)
# speedup vs baseline: 1.0105x; 1.0008x over previous
; __global__ void __launch_bounds__(NWAVES * 64, 2) fwd_kernel(Args args) {
;     ...
;     if (IN(2)) {
;     ...
;         for (int u2 = bx; u2 < BATCH * NCH / 2; u2 += G) { const int b2 = u2 / (NCH / 2), q0 = 2 * (u2 % (NCH / 2));
;             attn_unit(U, VT, Y, b2, q0, red, wave, lane); attn_unit(U, VT, Y, b2, q0 + 1, red, wave, lane); }
;     ...
;         { LruInv LV; lru_load_inv(LP, LV, wave, lane);
;         for (int u2 = bx; u2 < BATCH * NCH / 2; u2 += G) { const int b2 = u2 / (NCH / 2), c0 = 2 * (u2 % (NCH / 2));
;             lru_unit<1>(LP, LV, b2, c0, lds + wave * 16384, red, wave, lane, 0); lru_unit<1>(LP, LV, b2, c0 + 1, lds + wave * 16384, red, wave, lane, 1); } }
.LBB0_213:
	s_mov_b32 s101, 0
	s_cmp_lt_i32 s30, 3
	s_cselect_b64 s[4:5], -1, 0
	s_add_u32 s46, s28, 0x1a00000
	s_addc_u32 s47, s29, 0
	s_add_u32 s50, s28, 0x1b00000
	s_addc_u32 s51, s29, 0
	s_add_u32 s40, s28, 0x6000000
	s_addc_u32 s41, s29, 0
	s_and_b64 s[54:55], s[4:5], s[2:3]
	s_andn2_b64 vcc, exec, s[54:55]
	s_cbranch_vccnz .LBB0_341
	s_cmpk_lt_i32 s96, 0x100
	s_cselect_b64 s[56:57], -1, 0
	s_and_b64 vcc, exec, s[56:57]
	v_lshrrev_b32_e32 v173, 4, v206
	s_bitcmp1_b32 s96, 3
	s_cbranch_scc1 .Lp2_lru_first
	s_cbranch_vccnz .LBB0_216
	v_readlane_b32 s2, v238, 1
	v_lshrrev_b32_e32 v112, 4, v206
	s_and_b32 s4, s2, 0xffffffc0
	v_and_b32_e32 v172, 15, v207
	v_lshlrev_b32_e32 v174, 2, v112
	v_lshlrev_b32_e32 v176, 3, v112
	v_mov_b32_e32 v177, 0
	v_mov_b32_e32 v113, s4
	s_cbranch_execz .LBB0_217
	s_branch .LBB0_330
.Lp2_lru_first:
	s_mov_b32 s101, 1
	v_readlane_b32 s2, v238, 1
	v_lshrrev_b32_e32 v112, 4, v206
	s_and_b32 s4, s2, 0xffffffc0
	v_and_b32_e32 v172, 15, v207
	v_lshlrev_b32_e32 v174, 2, v112
	v_lshlrev_b32_e32 v176, 3, v112
	v_mov_b32_e32 v177, 0
	v_mov_b32_e32 v113, s4
	s_branch .LBB0_330

; __global__ void __launch_bounds__(NWAVES * 64, 2) fwd_kernel(Args args) {
;     ...
;     if (IN(2)) {
;     ...
;         for (int u2 = bx; u2 < BATCH * NCH / 2; u2 += G) { const int b2 = u2 / (NCH / 2), q0 = 2 * (u2 % (NCH / 2));
;             attn_unit(U, VT, Y, b2, q0, red, wave, lane); attn_unit(U, VT, Y, b2, q0 + 1, red, wave, lane); }
;     ...
;         { LruInv LV; lru_load_inv(LP, LV, wave, lane);
;         for (int u2 = bx; u2 < BATCH * NCH / 2; u2 += G) { const int b2 = u2 / (NCH / 2), c0 = 2 * (u2 % (NCH / 2));
;             lru_unit<1>(LP, LV, b2, c0, lds + wave * 16384, red, wave, lane, 0); lru_unit<1>(LP, LV, b2, c0 + 1, lds + wave * 16384, red, wave, lane, 1); } }
;     ...
;     }
.LBB0_341:
	s_cmp_eq_u32 s101, 1
	s_cbranch_scc0 .Lp2_done
	s_mov_b32 s101, 2
	s_add_u32 s0, s28, 0x12000000
	s_addc_u32 s1, s29, 0
	s_mov_b64 s[56:57], 0
	v_lshrrev_b32_e32 v173, 4, v206
	s_branch .LBB0_217
